# attention softmax: PV MFMAs re-spaced by issue cost (slip positions 5 and 12 of each 20-instruction group)
# speedup vs baseline: 1.0069x; 1.0045x over previous
.Latt_nogate:
	v_exp_f32_e32 v114, v114
	v_exp_f32_e32 v115, v115
	v_exp_f32_e32 v116, v116
	v_exp_f32_e32 v117, v117
	v_exp_f32_e32 v118, v118
	v_exp_f32_e32 v119, v119
	v_exp_f32_e32 v120, v120
	v_exp_f32_e32 v121, v121
	v_cvt_pk_bf16_f32 v66, v114, v115
	v_cvt_pk_bf16_f32 v67, v116, v117
	v_cvt_pk_bf16_f32 v68, v118, v119
	v_cvt_pk_bf16_f32 v69, v120, v121
	v_add_f32_e32 v178, v114, v115
	v_add_f32_e32 v179, v116, v117
	v_add_f32_e32 v180, v118, v119
	v_add_f32_e32 v181, v120, v121
	v_add_f32_e32 v178, v178, v179
	v_add_f32_e32 v180, v180, v181
	v_add_f32_e32 v178, v178, v180
	v_add_f32_e32 v210, v210, v178
	ds_read_b64_tr_b16 v[240:241], v185 offset:56320
	ds_read_b64_tr_b16 v[242:243], v185 offset:56832
	ds_read_b64_tr_b16 v[244:245], v185 offset:60416
	s_waitcnt lgkmcnt(11)
	ds_read_b64_tr_b16 v[246:247], v185 offset:60928
	ds_read_b64_tr_b16 v[114:115], v184 offset:53248
	ds_read_b64_tr_b16 v[116:117], v184 offset:53760
	ds_read_b64_tr_b16 v[118:119], v184 offset:57344
	s_waitcnt lgkmcnt(11)
	ds_read_b64_tr_b16 v[120:121], v184 offset:57856
	v_exp_f32_e32 v122, v122
	v_exp_f32_e32 v123, v123
	v_exp_f32_e32 v124, v124
	v_exp_f32_e32 v125, v125
	v_exp_f32_e32 v126, v126
	v_mfma_f32_32x32x16_bf16 v[34:49], v[66:69], v[216:219], v[34:49]
	v_exp_f32_e32 v127, v127
	v_exp_f32_e32 v128, v128
	v_exp_f32_e32 v129, v129
	v_cvt_pk_bf16_f32 v70, v122, v123
	v_cvt_pk_bf16_f32 v71, v124, v125
	v_cvt_pk_bf16_f32 v72, v126, v127
	v_cvt_pk_bf16_f32 v73, v128, v129
	v_mfma_f32_32x32x16_bf16 v[50:65], v[66:69], v[220:223], v[50:65]
	v_add_f32_e32 v178, v122, v123
	v_add_f32_e32 v179, v124, v125
	v_add_f32_e32 v180, v126, v127
	v_add_f32_e32 v181, v128, v129
	v_add_f32_e32 v178, v178, v179
	v_add_f32_e32 v180, v180, v181
	v_add_f32_e32 v178, v178, v180
	v_add_f32_e32 v210, v210, v178
	ds_read_b64_tr_b16 v[122:123], v184 offset:54272
	ds_read_b64_tr_b16 v[124:125], v184 offset:54784
	ds_read_b64_tr_b16 v[126:127], v184 offset:58368
	s_waitcnt lgkmcnt(11)
	ds_read_b64_tr_b16 v[128:129], v184 offset:58880
	v_exp_f32_e32 v98, v98
	v_exp_f32_e32 v99, v99
	v_exp_f32_e32 v100, v100
	v_exp_f32_e32 v101, v101
	v_exp_f32_e32 v102, v102
	v_mfma_f32_32x32x16_bf16 v[34:49], v[70:73], v[224:227], v[34:49]
	v_exp_f32_e32 v103, v103
	v_exp_f32_e32 v104, v104
	v_exp_f32_e32 v105, v105
	v_cvt_pk_bf16_f32 v74, v98, v99
	v_cvt_pk_bf16_f32 v75, v100, v101
	v_cvt_pk_bf16_f32 v76, v102, v103
	v_cvt_pk_bf16_f32 v77, v104, v105
	v_mfma_f32_32x32x16_bf16 v[50:65], v[70:73], v[228:231], v[50:65]
	v_add_f32_e32 v178, v98, v99
	v_add_f32_e32 v179, v100, v101
	v_add_f32_e32 v180, v102, v103
	v_add_f32_e32 v181, v104, v105
	v_add_f32_e32 v178, v178, v179
	v_add_f32_e32 v180, v180, v181
	v_add_f32_e32 v178, v178, v180
	v_add_f32_e32 v210, v210, v178
	ds_read_b64_tr_b16 v[98:99], v184 offset:55296
	ds_read_b64_tr_b16 v[100:101], v184 offset:55808
	ds_read_b64_tr_b16 v[102:103], v184 offset:59392
	s_waitcnt lgkmcnt(11)
	ds_read_b64_tr_b16 v[104:105], v184 offset:59904
	v_exp_f32_e32 v106, v106
	v_exp_f32_e32 v107, v107
	v_exp_f32_e32 v108, v108
	v_exp_f32_e32 v109, v109
	v_exp_f32_e32 v110, v110
	v_mfma_f32_32x32x16_bf16 v[34:49], v[74:77], v[232:235], v[34:49]
	v_exp_f32_e32 v111, v111
	v_exp_f32_e32 v112, v112
	v_exp_f32_e32 v113, v113
	v_cvt_pk_bf16_f32 v78, v106, v107
	v_cvt_pk_bf16_f32 v79, v108, v109
	v_cvt_pk_bf16_f32 v80, v110, v111
	v_cvt_pk_bf16_f32 v81, v112, v113
	v_mfma_f32_32x32x16_bf16 v[50:65], v[74:77], v[236:239], v[50:65]
	v_add_f32_e32 v178, v106, v107
	v_add_f32_e32 v179, v108, v109
	v_add_f32_e32 v180, v110, v111
	v_add_f32_e32 v181, v112, v113
	v_add_f32_e32 v178, v178, v179
	v_add_f32_e32 v180, v180, v181
	v_add_f32_e32 v178, v178, v180
	v_add_f32_e32 v210, v210, v178
	ds_read_b64_tr_b16 v[106:107], v184 offset:56320
	ds_read_b64_tr_b16 v[108:109], v184 offset:56832
	ds_read_b64_tr_b16 v[110:111], v184 offset:60416
	s_waitcnt lgkmcnt(11)
	ds_read_b64_tr_b16 v[112:113], v184 offset:60928
	v_exp_f32_e32 v2, v2
	v_exp_f32_e32 v3, v3
	v_exp_f32_e32 v4, v4
	v_exp_f32_e32 v5, v5
	v_exp_f32_e32 v6, v6
	v_mfma_f32_32x32x16_bf16 v[34:49], v[78:81], v[240:243], v[34:49]
	v_exp_f32_e32 v7, v7
	v_exp_f32_e32 v8, v8
	v_exp_f32_e32 v9, v9
	v_cvt_pk_bf16_f32 v66, v2, v3
	v_cvt_pk_bf16_f32 v67, v4, v5
	v_cvt_pk_bf16_f32 v68, v6, v7
	v_cvt_pk_bf16_f32 v69, v8, v9
	v_mfma_f32_32x32x16_bf16 v[50:65], v[78:81], v[244:247], v[50:65]
	v_add_f32_e32 v178, v2, v3
	v_add_f32_e32 v179, v4, v5
	v_add_f32_e32 v180, v6, v7
	v_add_f32_e32 v181, v8, v9
	v_add_f32_e32 v178, v178, v179
	v_add_f32_e32 v180, v180, v181
	v_add_f32_e32 v178, v178, v180
	v_add_f32_e32 v210, v210, v178
	v_exp_f32_e32 v10, v10
	v_exp_f32_e32 v11, v11
	v_exp_f32_e32 v12, v12
	v_exp_f32_e32 v13, v13
	v_exp_f32_e32 v14, v14
	v_mfma_f32_32x32x16_bf16 v[34:49], v[66:69], v[114:117], v[34:49]
	v_exp_f32_e32 v15, v15
	v_exp_f32_e32 v16, v16
	v_exp_f32_e32 v17, v17
	v_cvt_pk_bf16_f32 v70, v10, v11
	v_cvt_pk_bf16_f32 v71, v12, v13
	v_cvt_pk_bf16_f32 v72, v14, v15
	v_cvt_pk_bf16_f32 v73, v16, v17
	v_mfma_f32_32x32x16_bf16 v[50:65], v[66:69], v[118:121], v[50:65]
	v_add_f32_e32 v178, v10, v11
	v_add_f32_e32 v179, v12, v13
	v_add_f32_e32 v180, v14, v15
	v_add_f32_e32 v181, v16, v17
	v_add_f32_e32 v178, v178, v179
	v_add_f32_e32 v180, v180, v181
	v_add_f32_e32 v178, v178, v180
	v_add_f32_e32 v210, v210, v178
	v_exp_f32_e32 v18, v18
	v_exp_f32_e32 v19, v19
	v_exp_f32_e32 v20, v20
	v_exp_f32_e32 v21, v21
	v_exp_f32_e32 v22, v22
	s_waitcnt lgkmcnt(10)
	v_mfma_f32_32x32x16_bf16 v[34:49], v[70:73], v[122:125], v[34:49]
	v_exp_f32_e32 v23, v23
	v_exp_f32_e32 v24, v24
	v_exp_f32_e32 v25, v25
	v_cvt_pk_bf16_f32 v74, v18, v19
	v_cvt_pk_bf16_f32 v75, v20, v21
	v_cvt_pk_bf16_f32 v76, v22, v23
	v_cvt_pk_bf16_f32 v77, v24, v25
	s_waitcnt lgkmcnt(8)
	v_mfma_f32_32x32x16_bf16 v[50:65], v[70:73], v[126:129], v[50:65]
	v_add_f32_e32 v178, v18, v19
	v_add_f32_e32 v179, v20, v21
	v_add_f32_e32 v180, v22, v23
	v_add_f32_e32 v181, v24, v25
	v_add_f32_e32 v178, v178, v179
	v_add_f32_e32 v180, v180, v181
	v_add_f32_e32 v178, v178, v180
	v_add_f32_e32 v210, v210, v178
	v_exp_f32_e32 v26, v26
	v_exp_f32_e32 v27, v27
	v_exp_f32_e32 v28, v28
	v_exp_f32_e32 v29, v29
	v_exp_f32_e32 v30, v30
	s_waitcnt lgkmcnt(6)
	v_mfma_f32_32x32x16_bf16 v[34:49], v[74:77], v[98:101], v[34:49]
	v_exp_f32_e32 v31, v31
	v_exp_f32_e32 v32, v32
	v_exp_f32_e32 v33, v33
	v_cvt_pk_bf16_f32 v78, v26, v27
	v_cvt_pk_bf16_f32 v79, v28, v29
	v_cvt_pk_bf16_f32 v80, v30, v31
	v_cvt_pk_bf16_f32 v81, v32, v33
	s_waitcnt lgkmcnt(4)
	v_mfma_f32_32x32x16_bf16 v[50:65], v[74:77], v[102:105], v[50:65]
	v_add_f32_e32 v178, v26, v27
	v_add_f32_e32 v179, v28, v29
	v_add_f32_e32 v180, v30, v31
	v_add_f32_e32 v181, v32, v33
	v_add_f32_e32 v178, v178, v179
	v_add_f32_e32 v180, v180, v181
	v_add_f32_e32 v178, v178, v180
	v_add_f32_e32 v210, v210, v178
	s_waitcnt lgkmcnt(2)
	v_mfma_f32_32x32x16_bf16 v[34:49], v[78:81], v[106:109], v[34:49]
	s_waitcnt lgkmcnt(0)
	v_mfma_f32_32x32x16_bf16 v[50:65], v[78:81], v[110:113], v[50:65]
	s_cmp_eq_u32 s35, 0
	s_cbranch_scc1 .Latt_rs
	v_cmp_lt_f32_e32 vcc, 0x4b800000, v210
	s_cbranch_vccnz .Latt_rs
